# hand-written steady-state loop for differential attention units (in-place accumulators, ALiBi bias via MFMA C operand, conditional rescale) + FOX prologue loads batched
# speedup vs baseline: 1.0017x; 1.0017x over previous
.LBB0_390:
	s_and_b64 vcc, exec, s[16:17]
	s_cbranch_vccz .LBB0_407
	s_waitcnt vmcnt(0)
	s_mov_b32 s98, 0x3e8293ee
	v_cvt_f32_i32_e32 v205, v189
	v_mul_f32_e32 v206, 0x407af232, v200
	v_mov_b32_e32 v114, 0
	v_mul_f32_e32 v115, 0x3f800000, v206
	v_mul_f32_e32 v116, 0x40000000, v206
	v_mul_f32_e32 v117, 0x40400000, v206
	v_mul_f32_e32 v118, 0x41000000, v206
	v_mul_f32_e32 v119, 0x41100000, v206
	v_mul_f32_e32 v120, 0x41200000, v206
	v_mul_f32_e32 v121, 0x41300000, v206
	v_mul_f32_e32 v122, 0x41800000, v206
	v_mul_f32_e32 v123, 0x41880000, v206
	v_mul_f32_e32 v124, 0x41900000, v206
	v_mul_f32_e32 v125, 0x41980000, v206
	v_mul_f32_e32 v126, 0x41c00000, v206
	v_mul_f32_e32 v127, 0x41c80000, v206
	v_mul_f32_e32 v128, 0x41d00000, v206
	v_mul_f32_e32 v129, 0x41d80000, v206
.Ldf_iter:
	v_mfma_f32_32x32x16_bf16 v[2:17], v[170:173], v[130:133], v[114:129]
	v_mfma_f32_32x32x16_bf16 v[18:33], v[170:173], v[138:141], v[114:129]
	v_mfma_f32_32x32x16_bf16 v[2:17], v[174:177], v[134:137], v[2:17]
	v_mfma_f32_32x32x16_bf16 v[18:33], v[174:177], v[142:145], v[18:33]
	v_mul_f32_e64 v198, -v200, v205
	v_fmamk_f32 v199, v200, 0xc2000000, v198
	v_add_f32_e32 v205, 0x42000000, v205
	s_nop 7
	v_max3_f32 v206, v2, v3, v4
	v_max3_f32 v207, v5, v6, v7
	v_max3_f32 v208, v8, v9, v10
	v_max3_f32 v209, v11, v12, v13
	v_max3_f32 v206, v206, v14, v15
	v_max3_f32 v207, v207, v16, v17
	v_max3_f32 v206, v206, v207, v208
	v_max_f32_e32 v206, v206, v209
	v_fma_f32 v206, v206, s98, v198
	v_mov_b32_e32 v207, v206
	s_nop 1
	v_permlane32_swap_b32_e32 v206, v207
	v_max3_f32 v194, v188, v206, v207
	v_sub_f32_e32 v208, v188, v194
	v_sub_f32_e32 v196, v198, v194
	v_exp_f32_e32 v190, v208
	v_fma_f32 v2, v2, s98, v196
	v_fma_f32 v3, v3, s98, v196
	v_fma_f32 v4, v4, s98, v196
	v_fma_f32 v5, v5, s98, v196
	v_fma_f32 v6, v6, s98, v196
	v_fma_f32 v7, v7, s98, v196
	v_fma_f32 v8, v8, s98, v196
	v_fma_f32 v9, v9, s98, v196
	v_fma_f32 v10, v10, s98, v196
	v_fma_f32 v11, v11, s98, v196
	v_fma_f32 v12, v12, s98, v196
	v_fma_f32 v13, v13, s98, v196
	v_fma_f32 v14, v14, s98, v196
	v_fma_f32 v15, v15, s98, v196
	v_fma_f32 v16, v16, s98, v196
	v_fma_f32 v17, v17, s98, v196
	v_exp_f32_e32 v2, v2
	v_exp_f32_e32 v3, v3
	v_exp_f32_e32 v4, v4
	v_exp_f32_e32 v5, v5
	v_exp_f32_e32 v6, v6
	v_exp_f32_e32 v7, v7
	v_exp_f32_e32 v8, v8
	v_exp_f32_e32 v9, v9
	v_exp_f32_e32 v10, v10
	v_exp_f32_e32 v11, v11
	v_exp_f32_e32 v12, v12
	v_exp_f32_e32 v13, v13
	v_exp_f32_e32 v14, v14
	v_exp_f32_e32 v15, v15
	v_exp_f32_e32 v16, v16
	v_exp_f32_e32 v17, v17
	v_cmp_lt_f32_e32 vcc, v188, v194
	v_mov_b32_e32 v188, v194
	v_cvt_pk_bf16_f32 v98, v2, v3
	v_cvt_pk_bf16_f32 v99, v4, v5
	v_cvt_pk_bf16_f32 v100, v6, v7
	v_cvt_pk_bf16_f32 v101, v8, v9
	v_cvt_pk_bf16_f32 v102, v10, v11
	v_cvt_pk_bf16_f32 v103, v12, v13
	v_cvt_pk_bf16_f32 v104, v14, v15
	v_cvt_pk_bf16_f32 v105, v16, v17
	v_add_f32_e32 v206, v2, v3
	v_add_f32_e32 v207, v4, v5
	v_add_f32_e32 v208, v6, v7
	v_add_f32_e32 v209, v8, v9
	v_add_f32_e32 v206, v206, v10
	v_add_f32_e32 v207, v207, v11
	v_add_f32_e32 v208, v208, v12
	v_add_f32_e32 v209, v209, v13
	v_add_f32_e32 v206, v206, v14
	v_add_f32_e32 v207, v207, v15
	v_add_f32_e32 v208, v208, v16
	v_add_f32_e32 v209, v209, v17
	v_add_f32_e32 v206, v206, v207
	v_add_f32_e32 v208, v208, v209
	v_add_f32_e32 v206, v206, v208
	v_fmac_f32_e32 v206, v182, v190
	v_mov_b32_e32 v182, v206
	s_cbranch_vccz .Ldf_nr0
	v_pk_mul_f32 v[82:83], v[82:83], v[190:191] op_sel_hi:[1,0]
	v_pk_mul_f32 v[84:85], v[84:85], v[190:191] op_sel_hi:[1,0]
	v_pk_mul_f32 v[86:87], v[86:87], v[190:191] op_sel_hi:[1,0]
	v_pk_mul_f32 v[88:89], v[88:89], v[190:191] op_sel_hi:[1,0]
	v_pk_mul_f32 v[90:91], v[90:91], v[190:191] op_sel_hi:[1,0]
	v_pk_mul_f32 v[92:93], v[92:93], v[190:191] op_sel_hi:[1,0]
	v_pk_mul_f32 v[94:95], v[94:95], v[190:191] op_sel_hi:[1,0]
	v_pk_mul_f32 v[96:97], v[96:97], v[190:191] op_sel_hi:[1,0]
	v_pk_mul_f32 v[66:67], v[66:67], v[190:191] op_sel_hi:[1,0]
	v_pk_mul_f32 v[68:69], v[68:69], v[190:191] op_sel_hi:[1,0]
	v_pk_mul_f32 v[70:71], v[70:71], v[190:191] op_sel_hi:[1,0]
	v_pk_mul_f32 v[72:73], v[72:73], v[190:191] op_sel_hi:[1,0]
	v_pk_mul_f32 v[74:75], v[74:75], v[190:191] op_sel_hi:[1,0]
	v_pk_mul_f32 v[76:77], v[76:77], v[190:191] op_sel_hi:[1,0]
	v_pk_mul_f32 v[78:79], v[78:79], v[190:191] op_sel_hi:[1,0]
	v_pk_mul_f32 v[80:81], v[80:81], v[190:191] op_sel_hi:[1,0]
	s_nop 1
.Ldf_nr0:
	s_waitcnt vmcnt(2)
	v_mfma_f32_32x32x16_bf16 v[82:97], v[166:169], v[98:101], v[82:97]
	v_mfma_f32_32x32x16_bf16 v[66:81], v[158:161], v[98:101], v[66:81]
	v_mfma_f32_32x32x16_bf16 v[82:97], v[162:165], v[102:105], v[82:97]
	v_mfma_f32_32x32x16_bf16 v[66:81], v[154:157], v[102:105], v[66:81]
	v_max3_f32 v210, v18, v19, v20
	v_max3_f32 v211, v21, v22, v23
	v_max3_f32 v215, v24, v25, v26
	v_max3_f32 v216, v27, v28, v29
	v_max3_f32 v210, v210, v30, v31
	v_max3_f32 v211, v211, v32, v33
	v_max3_f32 v210, v210, v211, v215
	v_max_f32_e32 v210, v210, v216
	v_fma_f32 v210, v210, s98, v199
	v_mov_b32_e32 v211, v210
	s_nop 1
	v_permlane32_swap_b32_e32 v210, v211
	v_max3_f32 v195, v0, v210, v211
	v_sub_f32_e32 v215, v0, v195
	v_sub_f32_e32 v197, v199, v195
	v_exp_f32_e32 v192, v215
	v_fma_f32 v18, v18, s98, v197
	v_fma_f32 v19, v19, s98, v197
	v_fma_f32 v20, v20, s98, v197
	v_fma_f32 v21, v21, s98, v197
	v_fma_f32 v22, v22, s98, v197
	v_fma_f32 v23, v23, s98, v197
	v_fma_f32 v24, v24, s98, v197
	v_fma_f32 v25, v25, s98, v197
	v_fma_f32 v26, v26, s98, v197
	v_fma_f32 v27, v27, s98, v197
	v_fma_f32 v28, v28, s98, v197
	v_fma_f32 v29, v29, s98, v197
	v_fma_f32 v30, v30, s98, v197
	v_fma_f32 v31, v31, s98, v197
	v_fma_f32 v32, v32, s98, v197
	v_fma_f32 v33, v33, s98, v197
	v_exp_f32_e32 v18, v18
	v_exp_f32_e32 v19, v19
	v_exp_f32_e32 v20, v20
	v_exp_f32_e32 v21, v21
	v_exp_f32_e32 v22, v22
	v_exp_f32_e32 v23, v23
	v_exp_f32_e32 v24, v24
	v_exp_f32_e32 v25, v25
	v_exp_f32_e32 v26, v26
	v_exp_f32_e32 v27, v27
	v_exp_f32_e32 v28, v28
	v_exp_f32_e32 v29, v29
	v_exp_f32_e32 v30, v30
	v_exp_f32_e32 v31, v31
	v_exp_f32_e32 v32, v32
	v_exp_f32_e32 v33, v33
	v_cmp_lt_f32_e32 vcc, v0, v195
	v_mov_b32_e32 v0, v195
	v_cvt_pk_bf16_f32 v106, v18, v19
	v_cvt_pk_bf16_f32 v107, v20, v21
	v_cvt_pk_bf16_f32 v108, v22, v23
	v_cvt_pk_bf16_f32 v109, v24, v25
	v_cvt_pk_bf16_f32 v110, v26, v27
	v_cvt_pk_bf16_f32 v111, v28, v29
	v_cvt_pk_bf16_f32 v112, v30, v31
	v_cvt_pk_bf16_f32 v113, v32, v33
	v_add_f32_e32 v210, v18, v19
	v_add_f32_e32 v211, v20, v21
	v_add_f32_e32 v215, v22, v23
	v_add_f32_e32 v216, v24, v25
	v_add_f32_e32 v210, v210, v26
	v_add_f32_e32 v211, v211, v27
	v_add_f32_e32 v215, v215, v28
	v_add_f32_e32 v216, v216, v29
	v_add_f32_e32 v210, v210, v30
	v_add_f32_e32 v211, v211, v31
	v_add_f32_e32 v215, v215, v32
	v_add_f32_e32 v216, v216, v33
	v_add_f32_e32 v210, v210, v211
	v_add_f32_e32 v215, v215, v216
	v_add_f32_e32 v210, v210, v215
	v_fmac_f32_e32 v210, v183, v192
	v_mov_b32_e32 v183, v210
	s_cbranch_vccz .Ldf_nr1
	v_pk_mul_f32 v[50:51], v[50:51], v[192:193] op_sel_hi:[1,0]
	v_pk_mul_f32 v[52:53], v[52:53], v[192:193] op_sel_hi:[1,0]
	v_pk_mul_f32 v[54:55], v[54:55], v[192:193] op_sel_hi:[1,0]
	v_pk_mul_f32 v[56:57], v[56:57], v[192:193] op_sel_hi:[1,0]
	v_pk_mul_f32 v[58:59], v[58:59], v[192:193] op_sel_hi:[1,0]
	v_pk_mul_f32 v[60:61], v[60:61], v[192:193] op_sel_hi:[1,0]
	v_pk_mul_f32 v[62:63], v[62:63], v[192:193] op_sel_hi:[1,0]
	v_pk_mul_f32 v[64:65], v[64:65], v[192:193] op_sel_hi:[1,0]
	v_pk_mul_f32 v[34:35], v[34:35], v[192:193] op_sel_hi:[1,0]
	v_pk_mul_f32 v[36:37], v[36:37], v[192:193] op_sel_hi:[1,0]
	v_pk_mul_f32 v[38:39], v[38:39], v[192:193] op_sel_hi:[1,0]
	v_pk_mul_f32 v[40:41], v[40:41], v[192:193] op_sel_hi:[1,0]
	v_pk_mul_f32 v[42:43], v[42:43], v[192:193] op_sel_hi:[1,0]
	v_pk_mul_f32 v[44:45], v[44:45], v[192:193] op_sel_hi:[1,0]
	v_pk_mul_f32 v[46:47], v[46:47], v[192:193] op_sel_hi:[1,0]
	v_pk_mul_f32 v[48:49], v[48:49], v[192:193] op_sel_hi:[1,0]
	s_nop 1
.Ldf_nr1:
	v_mfma_f32_32x32x16_bf16 v[50:65], v[166:169], v[106:109], v[50:65]
	v_mfma_f32_32x32x16_bf16 v[34:49], v[158:161], v[106:109], v[34:49]
	v_mfma_f32_32x32x16_bf16 v[50:65], v[162:165], v[110:113], v[50:65]
	v_mfma_f32_32x32x16_bf16 v[34:49], v[154:157], v[110:113], v[34:49]
	s_and_b64 vcc, exec, s[4:5]
	s_cbranch_vccnz .Ldf_exit
	s_add_i32 s15, s15, -1
	v_lshl_add_u64 v[180:181], v[180:181], 0, s[84:85]
	s_cmp_le_i32 s15, s73
	s_cselect_b64 s[4:5], -1, 0
	s_add_i32 s100, s15, -1
	s_cmp_le_i32 s15, s73
	s_cselect_b32 s76, s15, s100
	s_lshl_b64 s[16:17], s[76:77], 12
	s_waitcnt vmcnt(0)
	v_mov_b32_e32 v170, v146
	v_mov_b32_e32 v171, v147
	v_mov_b32_e32 v172, v148
	v_mov_b32_e32 v173, v149
	v_mov_b32_e32 v174, v150
	v_mov_b32_e32 v175, v151
	v_mov_b32_e32 v176, v152
	v_mov_b32_e32 v177, v153
	global_load_dwordx4 v[166:169], v[180:181], off offset:-2048
	global_load_dwordx4 v[162:165], v[180:181], off offset:-1024
	global_load_dwordx4 v[158:161], v[180:181], off
	global_load_dwordx4 v[154:157], v[180:181], off offset:1024
	v_lshl_add_u64 v[220:221], v[178:179], 0, s[16:17]
	global_load_dwordx4 v[146:149], v[220:221], off
	global_load_dwordx4 v[150:153], v[220:221], off offset:1024
	s_branch .Ldf_iter
.Ldf_exit:
	s_waitcnt vmcnt(0)
	v_mov_b32_e32 v186, v182
	v_mov_b32_e32 v187, v183
	v_mov_b32_e32 v250, v188
	v_mov_b32_e32 v251, v0
	v_mov_b64_e32 v[2:3], v[82:83]
	v_mov_b64_e32 v[4:5], v[84:85]
	v_mov_b64_e32 v[6:7], v[86:87]
	v_mov_b64_e32 v[8:9], v[88:89]
	v_mov_b64_e32 v[10:11], v[90:91]
	v_mov_b64_e32 v[12:13], v[92:93]
	v_mov_b64_e32 v[14:15], v[94:95]
	v_mov_b64_e32 v[16:17], v[96:97]
	v_mov_b64_e32 v[18:19], v[66:67]
	v_mov_b64_e32 v[20:21], v[68:69]
	v_mov_b64_e32 v[22:23], v[70:71]
	v_mov_b64_e32 v[24:25], v[72:73]
	v_mov_b64_e32 v[26:27], v[74:75]
	v_mov_b64_e32 v[28:29], v[76:77]
	v_mov_b64_e32 v[30:31], v[78:79]
	v_mov_b64_e32 v[32:33], v[80:81]
	v_mov_b64_e32 v[98:99], v[50:51]
	v_mov_b64_e32 v[100:101], v[52:53]
	v_mov_b64_e32 v[102:103], v[54:55]
	v_mov_b64_e32 v[104:105], v[56:57]
	v_mov_b64_e32 v[106:107], v[58:59]
	v_mov_b64_e32 v[108:109], v[60:61]
	v_mov_b64_e32 v[110:111], v[62:63]
	v_mov_b64_e32 v[112:113], v[64:65]
	v_mov_b64_e32 v[114:115], v[34:35]
	v_mov_b64_e32 v[116:117], v[36:37]
	v_mov_b64_e32 v[118:119], v[38:39]
	v_mov_b64_e32 v[120:121], v[40:41]
	v_mov_b64_e32 v[122:123], v[42:43]
	v_mov_b64_e32 v[124:125], v[44:45]
	v_mov_b64_e32 v[126:127], v[46:47]
	v_mov_b64_e32 v[128:129], v[48:49]
	s_add_i32 s15, s15, -1
	s_branch .LBB0_411

.LBB0_412:
	s_movk_i32 s4, 0x84
	v_mul_lo_u32 v0, v247, s4
	v_cmp_ge_i32_e32 vcc, s14, v247
	v_mov_b32_e32 v5, 0
	v_add_u32_e32 v0, s49, v0
	s_and_saveexec_b64 s[16:17], vcc
	s_cbranch_execz .LBB0_415
	s_load_dwordx2 s[4:5], s[0:1], 0x18
	v_readlane_b32 s6, v254, 58
	s_or_b32 s76, s34, s6
	s_lshl_b64 s[6:7], s[76:77], 2
	v_lshlrev_b32_e32 v2, 5, v247
	s_waitcnt lgkmcnt(0)
	s_add_u32 s4, s4, s6
	s_addc_u32 s5, s5, s7
	global_load_dword v4, v1, s[4:5]
	s_lshl_b32 s3, s3, 13
	s_and_b32 s3, s3, 0x18000
	s_lshl_b32 s4, s34, 2
	s_add_u32 s4, s54, s4
	s_addc_u32 s5, s55, 0
	s_add_u32 s4, s4, s3
	v_ashrrev_i32_e32 v3, 31, v2
	s_addc_u32 s5, s5, 0
	v_lshl_add_u64 v[2:3], v[2:3], 4, s[4:5]
	s_mov_b64 s[4:5], 0x7780040
	v_lshl_add_u64 v[2:3], v[2:3], 0, s[4:5]
	v_mov_b32_e32 v5, 0
	s_mov_b32 s3, 0
	global_load_dword v142, v[2:3], off offset:-64
	global_load_dword v143, v[2:3], off offset:-48
	global_load_dword v144, v[2:3], off offset:-32
	global_load_dword v145, v[2:3], off offset:-16
	global_load_dword v146, v[2:3], off
	global_load_dword v147, v[2:3], off offset:16
	global_load_dword v148, v[2:3], off offset:32
	global_load_dword v149, v[2:3], off offset:48
	global_load_dword v150, v[2:3], off offset:64
	global_load_dword v151, v[2:3], off offset:80
	global_load_dword v152, v[2:3], off offset:96
	global_load_dword v153, v[2:3], off offset:112
	global_load_dword v154, v[2:3], off offset:128
	global_load_dword v155, v[2:3], off offset:144
	global_load_dword v156, v[2:3], off offset:160
	global_load_dword v157, v[2:3], off offset:176
	global_load_dword v158, v[2:3], off offset:192
	global_load_dword v159, v[2:3], off offset:208
	global_load_dword v168, v[2:3], off offset:224
	global_load_dword v169, v[2:3], off offset:240
	global_load_dword v170, v[2:3], off offset:256
	global_load_dword v171, v[2:3], off offset:272
	global_load_dword v172, v[2:3], off offset:288
	global_load_dword v173, v[2:3], off offset:304
	global_load_dword v174, v[2:3], off offset:320
	global_load_dword v175, v[2:3], off offset:336
	global_load_dword v176, v[2:3], off offset:352
	global_load_dword v177, v[2:3], off offset:368
	global_load_dword v178, v[2:3], off offset:384
	global_load_dword v179, v[2:3], off offset:400
	global_load_dword v180, v[2:3], off offset:416
	global_load_dword v181, v[2:3], off offset:432
	s_waitcnt vmcnt(0)
.LBB0_414:
	v_add_f32_e32 v6, v4, v142
	v_min_f32_e32 v7, 0, v6
	v_mul_f32_e64 v6, |v6|, s86
	v_exp_f32_e32 v6, v6
	s_nop 0
	v_add_f32_e32 v6, 1.0, v6
	v_cmp_gt_f32_e64 s[4:5], s90, v6
	s_nop 1
	v_cndmask_b32_e64 v8, 0, 32, s[4:5]
	v_ldexp_f32 v6, v6, v8
	v_log_f32_e32 v6, v6
	s_nop 0
	v_mul_f32_e32 v8, 0x3f317217, v6
	v_fma_f32 v8, v6, s91, -v8
	v_fmac_f32_e32 v8, 0x3377d1cf, v6
	v_fmac_f32_e32 v8, 0x3f317217, v6
	v_cmp_lt_f32_e64 s[6:7], |v6|, s30
	s_nop 1
	v_cndmask_b32_e64 v6, v6, v8, s[6:7]
	v_cndmask_b32_e64 v8, 0, v244, s[4:5]
	v_sub_f32_e32 v6, v6, v8
	v_sub_f32_e32 v6, v7, v6
	v_add_f32_e32 v5, v5, v6
	v_add_u32_e32 v6, s3, v0
	s_add_i32 s3, s3, 32
	s_cmpk_lg_i32 s3, 0x80
	v_add_f32_e32 v7, v4, v143
	v_min_f32_e32 v8, 0, v7
	v_mul_f32_e64 v7, |v7|, s86
	v_exp_f32_e32 v7, v7
	s_nop 0
	v_add_f32_e32 v7, 1.0, v7
	v_cmp_gt_f32_e64 s[4:5], s90, v7
	s_nop 1
	v_cndmask_b32_e64 v9, 0, 32, s[4:5]
	v_ldexp_f32 v7, v7, v9
	v_log_f32_e32 v7, v7
	s_nop 0
	v_mul_f32_e32 v9, 0x3f317217, v7
	v_fma_f32 v9, v7, s91, -v9
	v_fmac_f32_e32 v9, 0x3377d1cf, v7
	v_fmac_f32_e32 v9, 0x3f317217, v7
	v_cmp_lt_f32_e64 s[6:7], |v7|, s30
	s_nop 1
	v_cndmask_b32_e64 v7, v7, v9, s[6:7]
	v_cndmask_b32_e64 v9, 0, v244, s[4:5]
	v_sub_f32_e32 v7, v7, v9
	v_sub_f32_e32 v7, v8, v7
	v_add_f32_e32 v7, v5, v7
	ds_write2_b32 v6, v5, v7 offset1:1
	v_add_f32_e32 v5, v4, v144
	v_min_f32_e32 v8, 0, v5
	v_mul_f32_e64 v5, |v5|, s86
	v_exp_f32_e32 v5, v5
	s_nop 0
	v_add_f32_e32 v5, 1.0, v5
	v_cmp_gt_f32_e64 s[4:5], s90, v5
	s_nop 1
	v_cndmask_b32_e64 v9, 0, 32, s[4:5]
	v_ldexp_f32 v5, v5, v9
	v_log_f32_e32 v5, v5
	s_nop 0
	v_mul_f32_e32 v9, 0x3f317217, v5
	v_fma_f32 v9, v5, s91, -v9
	v_fmac_f32_e32 v9, 0x3377d1cf, v5
	v_fmac_f32_e32 v9, 0x3f317217, v5
	v_cmp_lt_f32_e64 s[6:7], |v5|, s30
	s_nop 1
	v_cndmask_b32_e64 v5, v5, v9, s[6:7]
	v_cndmask_b32_e64 v9, 0, v244, s[4:5]
	v_sub_f32_e32 v5, v5, v9
	v_sub_f32_e32 v5, v8, v5
	v_add_f32_e32 v5, v7, v5
	v_add_f32_e32 v7, v4, v145
	v_min_f32_e32 v8, 0, v7
	v_mul_f32_e64 v7, |v7|, s86
	v_exp_f32_e32 v7, v7
	s_nop 0
	v_add_f32_e32 v7, 1.0, v7
	v_cmp_gt_f32_e64 s[4:5], s90, v7
	s_nop 1
	v_cndmask_b32_e64 v9, 0, 32, s[4:5]
	v_ldexp_f32 v7, v7, v9
	v_log_f32_e32 v7, v7
	s_nop 0
	v_mul_f32_e32 v9, 0x3f317217, v7
	v_fma_f32 v9, v7, s91, -v9
	v_fmac_f32_e32 v9, 0x3377d1cf, v7
	v_fmac_f32_e32 v9, 0x3f317217, v7
	v_cmp_lt_f32_e64 s[6:7], |v7|, s30
	s_nop 1
	v_cndmask_b32_e64 v7, v7, v9, s[6:7]
	v_cndmask_b32_e64 v9, 0, v244, s[4:5]
	v_sub_f32_e32 v7, v7, v9
	v_sub_f32_e32 v7, v8, v7
	v_add_f32_e32 v7, v5, v7
	ds_write2_b32 v6, v5, v7 offset0:2 offset1:3
	v_add_f32_e32 v5, v4, v146
	v_min_f32_e32 v8, 0, v5
	v_mul_f32_e64 v5, |v5|, s86
	v_exp_f32_e32 v5, v5
	s_nop 0
	v_add_f32_e32 v5, 1.0, v5
	v_cmp_gt_f32_e64 s[4:5], s90, v5
	s_nop 1
	v_cndmask_b32_e64 v9, 0, 32, s[4:5]
	v_ldexp_f32 v5, v5, v9
	v_log_f32_e32 v5, v5
	s_nop 0
	v_mul_f32_e32 v9, 0x3f317217, v5
	v_fma_f32 v9, v5, s91, -v9
	v_fmac_f32_e32 v9, 0x3377d1cf, v5
	v_fmac_f32_e32 v9, 0x3f317217, v5
	v_cmp_lt_f32_e64 s[6:7], |v5|, s30
	s_nop 1
	v_cndmask_b32_e64 v5, v5, v9, s[6:7]
	v_cndmask_b32_e64 v9, 0, v244, s[4:5]
	v_sub_f32_e32 v5, v5, v9
	v_sub_f32_e32 v5, v8, v5
	v_add_f32_e32 v5, v7, v5
	v_add_f32_e32 v7, v4, v147
	v_min_f32_e32 v8, 0, v7
	v_mul_f32_e64 v7, |v7|, s86
	v_exp_f32_e32 v7, v7
	s_nop 0
	v_add_f32_e32 v7, 1.0, v7
	v_cmp_gt_f32_e64 s[4:5], s90, v7
	s_nop 1
	v_cndmask_b32_e64 v9, 0, 32, s[4:5]
	v_ldexp_f32 v7, v7, v9
	v_log_f32_e32 v7, v7
	s_nop 0
	v_mul_f32_e32 v9, 0x3f317217, v7
	v_fma_f32 v9, v7, s91, -v9
	v_fmac_f32_e32 v9, 0x3377d1cf, v7
	v_fmac_f32_e32 v9, 0x3f317217, v7
	v_cmp_lt_f32_e64 s[6:7], |v7|, s30
	s_nop 1
	v_cndmask_b32_e64 v7, v7, v9, s[6:7]
	v_cndmask_b32_e64 v9, 0, v244, s[4:5]
	v_sub_f32_e32 v7, v7, v9
	v_sub_f32_e32 v7, v8, v7
	v_add_f32_e32 v7, v5, v7
	ds_write2_b32 v6, v5, v7 offset0:4 offset1:5
	v_add_f32_e32 v5, v4, v148
	v_min_f32_e32 v8, 0, v5
	v_mul_f32_e64 v5, |v5|, s86
	v_exp_f32_e32 v5, v5
	s_nop 0
	v_add_f32_e32 v5, 1.0, v5
	v_cmp_gt_f32_e64 s[4:5], s90, v5
	s_nop 1
	v_cndmask_b32_e64 v9, 0, 32, s[4:5]
	v_ldexp_f32 v5, v5, v9
	v_log_f32_e32 v5, v5
	s_nop 0
	v_mul_f32_e32 v9, 0x3f317217, v5
	v_fma_f32 v9, v5, s91, -v9
	v_fmac_f32_e32 v9, 0x3377d1cf, v5
	v_fmac_f32_e32 v9, 0x3f317217, v5
	v_cmp_lt_f32_e64 s[6:7], |v5|, s30
	s_nop 1
	v_cndmask_b32_e64 v5, v5, v9, s[6:7]
	v_cndmask_b32_e64 v9, 0, v244, s[4:5]
	v_sub_f32_e32 v5, v5, v9
	v_sub_f32_e32 v5, v8, v5
	v_add_f32_e32 v7, v7, v5
	v_add_f32_e32 v5, v4, v149
	v_min_f32_e32 v8, 0, v5
	v_mul_f32_e64 v5, |v5|, s86
	v_exp_f32_e32 v5, v5
	s_nop 0
	v_add_f32_e32 v5, 1.0, v5
	v_cmp_gt_f32_e64 s[4:5], s90, v5
	s_nop 1
	v_cndmask_b32_e64 v9, 0, 32, s[4:5]
	v_ldexp_f32 v5, v5, v9
	v_log_f32_e32 v5, v5
	s_nop 0
	v_mul_f32_e32 v9, 0x3f317217, v5
	v_fma_f32 v9, v5, s91, -v9
	v_fmac_f32_e32 v9, 0x3377d1cf, v5
	v_fmac_f32_e32 v9, 0x3f317217, v5
	v_cmp_lt_f32_e64 s[6:7], |v5|, s30
	s_nop 1
	v_cndmask_b32_e64 v5, v5, v9, s[6:7]
	v_cndmask_b32_e64 v9, 0, v244, s[4:5]
	v_sub_f32_e32 v5, v5, v9
	v_sub_f32_e32 v5, v8, v5
	v_add_f32_e32 v5, v7, v5
	ds_write2_b32 v6, v7, v5 offset0:6 offset1:7
	v_mov_b32_e32 v142, v150
	v_mov_b32_e32 v143, v151
	v_mov_b32_e32 v144, v152
	v_mov_b32_e32 v145, v153
	v_mov_b32_e32 v146, v154
	v_mov_b32_e32 v147, v155
	v_mov_b32_e32 v148, v156
	v_mov_b32_e32 v149, v157
	v_mov_b32_e32 v150, v158
	v_mov_b32_e32 v151, v159
	v_mov_b32_e32 v152, v168
	v_mov_b32_e32 v153, v169
	v_mov_b32_e32 v154, v170
	v_mov_b32_e32 v155, v171
	v_mov_b32_e32 v156, v172
	v_mov_b32_e32 v157, v173
	v_mov_b32_e32 v158, v174
	v_mov_b32_e32 v159, v175
	v_mov_b32_e32 v168, v176
	v_mov_b32_e32 v169, v177
	v_mov_b32_e32 v170, v178
	v_mov_b32_e32 v171, v179
	v_mov_b32_e32 v172, v180
	v_mov_b32_e32 v173, v181
	s_cbranch_scc1 .LBB0_414

	.amdhsa_kernel _Z8fwd_mega6Params
		.amdhsa_group_segment_fixed_size 0
		.amdhsa_private_segment_fixed_size 0
		.amdhsa_kernarg_size 392
		.amdhsa_user_sgpr_count 2
		.amdhsa_user_sgpr_dispatch_ptr 0
		.amdhsa_user_sgpr_queue_ptr 0
		.amdhsa_user_sgpr_kernarg_segment_ptr 1
		.amdhsa_user_sgpr_dispatch_id 0
		.amdhsa_user_sgpr_kernarg_preload_length 0
		.amdhsa_user_sgpr_kernarg_preload_offset 0
		.amdhsa_user_sgpr_private_segment_size 0
		.amdhsa_uses_dynamic_stack 0
		.amdhsa_enable_private_segment 0
		.amdhsa_system_sgpr_workgroup_id_x 1
		.amdhsa_system_sgpr_workgroup_id_y 0
		.amdhsa_system_sgpr_workgroup_id_z 0
		.amdhsa_system_sgpr_workgroup_info 0
		.amdhsa_system_vgpr_workitem_id 2
		.amdhsa_next_free_vgpr 256
		.amdhsa_next_free_sgpr 102
		.amdhsa_accum_offset 256
		.amdhsa_reserve_vcc 1
		.amdhsa_float_round_mode_32 0
		.amdhsa_float_round_mode_16_64 0
		.amdhsa_float_denorm_mode_32 3
		.amdhsa_float_denorm_mode_16_64 3
		.amdhsa_dx10_clamp 1
		.amdhsa_ieee_mode 1
		.amdhsa_fp16_overflow 0
		.amdhsa_tg_split 0
		.amdhsa_exception_fp_ieee_invalid_op 0
		.amdhsa_exception_fp_denorm_src 0
		.amdhsa_exception_fp_ieee_div_zero 0
		.amdhsa_exception_fp_ieee_overflow 0
		.amdhsa_exception_fp_ieee_underflow 0
		.amdhsa_exception_fp_ieee_inexact 0
		.amdhsa_exception_int_div_zero 0
	.end_amdhsa_kernel

.Lfunc_end0:
	.size	_Z8fwd_mega6Params, .Lfunc_end0-_Z8fwd_mega6Params
	.set _Z8fwd_mega6Params.num_vgpr, 256
	.set _Z8fwd_mega6Params.num_agpr, 0
	.set _Z8fwd_mega6Params.numbered_sgpr, 102
	.set _Z8fwd_mega6Params.num_named_barrier, 0
	.set _Z8fwd_mega6Params.private_seg_size, 0
	.set _Z8fwd_mega6Params.uses_vcc, 1
	.set _Z8fwd_mega6Params.uses_flat_scratch, 0
	.set _Z8fwd_mega6Params.has_dyn_sized_stack, 0
	.set _Z8fwd_mega6Params.has_recursion, 0
	.set _Z8fwd_mega6Params.has_indirect_call, 0

amdhsa.kernels:
  - .agpr_count:     0
    .args:
      - .offset:         0
        .size:           136
        .value_kind:     by_value
      - .offset:         136
        .size:           4
        .value_kind:     hidden_block_count_x
      - .offset:         140
        .size:           4
        .value_kind:     hidden_block_count_y
      - .offset:         144
        .size:           4
        .value_kind:     hidden_block_count_z
      - .offset:         148
        .size:           2
        .value_kind:     hidden_group_size_x
      - .offset:         150
        .size:           2
        .value_kind:     hidden_group_size_y
      - .offset:         152
        .size:           2
        .value_kind:     hidden_group_size_z
      - .offset:         154
        .size:           2
        .value_kind:     hidden_remainder_x
      - .offset:         156
        .size:           2
        .value_kind:     hidden_remainder_y
      - .offset:         158
        .size:           2
        .value_kind:     hidden_remainder_z
      - .offset:         176
        .size:           8
        .value_kind:     hidden_global_offset_x
      - .offset:         184
        .size:           8
        .value_kind:     hidden_global_offset_y
      - .offset:         192
        .size:           8
        .value_kind:     hidden_global_offset_z
      - .offset:         200
        .size:           2
        .value_kind:     hidden_grid_dims
      - .offset:         224
        .size:           8
        .value_kind:     hidden_multigrid_sync_arg
      - .offset:         256
        .size:           4
        .value_kind:     hidden_dynamic_lds_size
    .group_segment_fixed_size: 0
    .kernarg_segment_align: 8
    .kernarg_segment_size: 392
    .language:       OpenCL C
    .language_version:
      - 2
      - 0
    .max_flat_workgroup_size: 512
    .name:           _Z8fwd_mega6Params
    .private_segment_fixed_size: 0
    .sgpr_count:     108
    .sgpr_spill_count: 68
    .symbol:         _Z8fwd_mega6Params.kd
    .uniform_work_group_size: 1
    .uses_dynamic_stack: false
    .vgpr_count:     256
    .vgpr_spill_count: 0
    .wavefront_size: 64
